# baseline (speedup 1.0000x reference)
; __device__ __forceinline__ void attn_a_phase(const bf16_t* __restrict__ qkv, bf16_t* __restrict__ att, const float* __restrict__ sinks) {
;     ...
;   for (int item = blockIdx.x; item < 512; item += gridDim.x) {
;     const int it = (item & ~255) | ((item & 7) << 5) | ((item & 255) >> 3);
;     const int nb = it & 31, hkv = (it >> 5) & 3, b = it >> 7;
;     const int t0 = b * SEQ + nb * 128;
;     const int head = hkv * 8 + wid;
;     __syncthreads();
; #pragma unroll
;     for (int i = 0; i < 4; ++i) {
;       const int u = tid + i * NTHR, key = u >> 3, part = u & 7;
;       u32x4 kv = {0u, 0u, 0u, 0u};
;       if (nb > 0 || key >= 128) kv = *(const u32x4*)(qkv + (size_t)(t0 - 128 + key) * NQA + 2048 + hkv * 64 + part * 8);
;       *(u32x4*)(Ks + key * 72 + part * 8) = kv;
;     }
.LBB0_322:
	s_lshl_b32 s19, s26, 5
	s_and_b32 s0, s26, 0x7ffff00
	s_and_b32 s1, s19, 0x80
	s_or_b32 s0, s1, s0
	s_bfe_u32 s16, s26, 0x50003
	s_lshl_b32 s0, s0, 5
	s_lshl_b32 s1, s16, 7
	s_and_b32 s18, s26, 3
	s_or_b32 s17, s0, s1
	s_cmp_lg_u32 s16, 0
	s_cselect_b64 s[0:1], -1, 0
	s_add_i32 s23, s17, 0xffffff80
	s_lshl_b32 s22, s18, 6
	s_or_b64 s[28:29], s[4:5], s[0:1]
	v_mov_b32_e32 v0, 0
	v_lshlrev_b32_e32 v8, 1, v52
	v_mov_b32_e32 v2, 0
	v_mov_b32_e32 v3, 0
	v_mov_b32_e32 v4, 0
	v_mov_b32_e32 v5, 0
	s_barrier
	v_mov_b32_e32 v240, 0
	v_mov_b32_e32 v241, 0
	v_mov_b32_e32 v242, 0
	v_mov_b32_e32 v243, 0
	s_and_saveexec_b64 s[2:3], s[28:29]
	s_cbranch_execz .LBB0_324
	v_add_u32_e32 v1, s23, v83
	v_mov_b64_e32 v[2:3], s[46:47]
	v_mad_i64_i32 v[2:3], s[28:29], v1, s55, v[2:3]
	s_lshl_b32 s86, s22, 1
	v_lshl_add_u64 v[2:3], v[2:3], 0, s[86:87]
	v_mov_b32_e32 v9, v129
	v_lshl_add_u64 v[2:3], v[2:3], 0, v[8:9]
	v_add_co_u32_e32 v2, vcc, 0x1000, v2
	v_readlane_b32 s44, v234, 14
	s_nop 0
	v_addc_co_u32_e32 v3, vcc, 0, v3, vcc
	global_load_dwordx4 v[240:243], v[2:3], off
.LBB0_324:
	s_or_b64 exec, exec, s[2:3]

; __device__ __forceinline__ void attn_a_phase(const bf16_t* __restrict__ qkv, bf16_t* __restrict__ att, const float* __restrict__ sinks) {
;     ...
;     for (int i = 0; i < 4; ++i) {
;       const int u = tid + i * NTHR, key = u >> 3, part = u & 7;
;       u32x4 kv = {0u, 0u, 0u, 0u};
;       if (nb > 0 || key >= 128) kv = *(const u32x4*)(qkv + (size_t)(t0 - 128 + key) * NQA + 2048 + hkv * 64 + part * 8);
;       *(u32x4*)(Ks + key * 72 + part * 8) = kv;
;     }
	s_or_b64 s[28:29], s[0:1], s[6:7]
	v_mov_b32_e32 v2, 0
	v_mov_b32_e32 v3, 0
	v_mov_b32_e32 v4, 0
	v_mov_b32_e32 v5, 0
	v_mov_b32_e32 v244, 0
	v_mov_b32_e32 v245, 0
	v_mov_b32_e32 v246, 0
	v_mov_b32_e32 v247, 0
	s_and_saveexec_b64 s[2:3], s[28:29]
	s_cbranch_execz .LBB0_326
	v_add_u32_e32 v1, s23, v84
	v_mov_b64_e32 v[2:3], s[46:47]
	v_mad_i64_i32 v[2:3], s[28:29], v1, s55, v[2:3]
	s_lshl_b32 s86, s22, 1
	v_lshl_add_u64 v[2:3], v[2:3], 0, s[86:87]
	v_mov_b32_e32 v9, v129
	v_lshl_add_u64 v[2:3], v[2:3], 0, v[8:9]
	v_add_co_u32_e32 v2, vcc, 0x1000, v2
	v_readlane_b32 s44, v234, 14
	s_nop 0
	v_addc_co_u32_e32 v3, vcc, 0, v3, vcc
	global_load_dwordx4 v[244:247], v[2:3], off
.LBB0_326:
	s_or_b64 exec, exec, s[2:3]

; __device__ __forceinline__ void attn_a_phase(const bf16_t* __restrict__ qkv, bf16_t* __restrict__ att, const float* __restrict__ sinks) {
;     ...
;     for (int i = 0; i < 4; ++i) {
;       const int u = tid + i * NTHR, key = u >> 3, part = u & 7;
;       u32x4 kv = {0u, 0u, 0u, 0u};
;       if (nb > 0 || key >= 128) kv = *(const u32x4*)(qkv + (size_t)(t0 - 128 + key) * NQA + 2048 + hkv * 64 + part * 8);
;       *(u32x4*)(Ks + key * 72 + part * 8) = kv;
;     }
	s_or_b64 s[28:29], s[0:1], s[8:9]
	v_mov_b32_e32 v1, 0
	v_mov_b32_e32 v2, 0
	v_mov_b32_e32 v3, 0
	v_mov_b32_e32 v248, 0
	v_mov_b32_e32 v249, 0
	v_mov_b32_e32 v250, 0
	v_mov_b32_e32 v251, 0
	s_and_saveexec_b64 s[2:3], s[28:29]
	s_cbranch_execz .LBB0_328
	v_add_u32_e32 v2, s23, v85
	v_mov_b64_e32 v[0:1], s[46:47]
	v_mad_i64_i32 v[0:1], s[28:29], v2, s55, v[0:1]
	s_lshl_b32 s86, s22, 1
	v_lshl_add_u64 v[0:1], v[0:1], 0, s[86:87]
	v_mov_b32_e32 v9, v129
	v_lshl_add_u64 v[0:1], v[0:1], 0, v[8:9]
	v_add_co_u32_e32 v0, vcc, 0x1000, v0
	v_readlane_b32 s44, v234, 14
	s_nop 0
	v_addc_co_u32_e32 v1, vcc, 0, v1, vcc
	global_load_dwordx4 v[248:251], v[0:1], off
.LBB0_328:
	s_or_b64 exec, exec, s[2:3]

; __device__ __forceinline__ void attn_a_phase(const bf16_t* __restrict__ qkv, bf16_t* __restrict__ att, const float* __restrict__ sinks) {
;     ...
;     for (int i = 0; i < 4; ++i) {
;       const int u = tid + i * NTHR, key = u >> 3, part = u & 7;
;       u32x4 kv = {0u, 0u, 0u, 0u};
;       if (nb > 0 || key >= 128) kv = *(const u32x4*)(qkv + (size_t)(t0 - 128 + key) * NQA + 2048 + hkv * 64 + part * 8);
;       *(u32x4*)(Ks + key * 72 + part * 8) = kv;
;     }
	s_or_b64 s[28:29], s[0:1], s[10:11]
	v_mov_b32_e32 v0, 0
	v_mov_b32_e32 v2, 0
	v_mov_b32_e32 v3, 0
	v_mov_b32_e32 v4, 0
	v_mov_b32_e32 v5, 0
	v_mov_b32_e32 v252, 0
	v_mov_b32_e32 v253, 0
	v_mov_b32_e32 v254, 0
	v_mov_b32_e32 v255, 0
	s_and_saveexec_b64 s[2:3], s[28:29]
	s_cbranch_execz .LBB0_330
	v_add_u32_e32 v1, s23, v86
	v_mov_b64_e32 v[2:3], s[46:47]
	v_mad_i64_i32 v[2:3], s[28:29], v1, s55, v[2:3]
	s_lshl_b32 s86, s22, 1
	v_lshl_add_u64 v[2:3], v[2:3], 0, s[86:87]
	v_mov_b32_e32 v9, v129
	v_lshl_add_u64 v[2:3], v[2:3], 0, v[8:9]
	v_add_co_u32_e32 v2, vcc, 0x1000, v2
	v_readlane_b32 s44, v234, 14
	s_nop 0
	v_addc_co_u32_e32 v3, vcc, 0, v3, vcc
	global_load_dwordx4 v[252:255], v[2:3], off
.LBB0_330:
	s_or_b64 exec, exec, s[2:3]
	s_waitcnt vmcnt(0)
	ds_write_b128 v92, v[240:243]
	ds_write_b128 v93, v[244:247]
	ds_write_b128 v94, v[248:251]
	ds_write_b128 v95, v[252:255]

; __device__ __forceinline__ void attn_a_phase(const bf16_t* __restrict__ qkv, bf16_t* __restrict__ att, const float* __restrict__ sinks) {
;     ...
;     for (int i = 0; i < 2; ++i) {
;       const int u = tid + i * NTHR, kp = u >> 3, part = u & 7;
;       u32x4 va = {0u, 0u, 0u, 0u}, vb = {0u, 0u, 0u, 0u};
;       if (nb > 0 || kp >= 64) {
;         va = *(const u32x4*)(qkv + (size_t)(t0 - 128 + 2 * kp) * NQA + 2304 + hkv * 64 + part * 8);
;         vb = *(const u32x4*)(qkv + (size_t)(t0 - 128 + 2 * kp + 1) * NQA + 2304 + hkv * 64 + part * 8);
;       }
	s_or_b64 s[28:29], s[12:13], s[0:1]
	v_mov_b32_e32 v1, 0
	v_mov_b32_e32 v2, 0
	v_mov_b32_e32 v3, 0
	v_mov_b32_e32 v4, 0
	v_mov_b32_e32 v5, 0
	v_mov_b32_e32 v6, 0
	v_mov_b32_e32 v7, 0
	s_and_saveexec_b64 s[2:3], s[28:29]
	s_cbranch_execz .LBB0_332
	v_add_u32_e32 v4, s23, v87
	v_mov_b64_e32 v[0:1], s[46:47]
	v_mad_i64_i32 v[2:3], s[28:29], v4, s55, v[0:1]
	s_lshl_b32 s86, s22, 1
	v_lshl_add_u64 v[2:3], v[2:3], 0, s[86:87]
	v_mov_b32_e32 v9, v129
	v_or_b32_e32 v4, 1, v4
	v_lshl_add_u64 v[2:3], v[2:3], 0, v[8:9]
	v_mad_i64_i32 v[0:1], s[28:29], v4, s55, v[0:1]
	v_add_co_u32_e32 v2, vcc, 0x1000, v2
	v_lshl_add_u64 v[0:1], v[0:1], 0, s[86:87]
	s_nop 0
	v_addc_co_u32_e32 v3, vcc, 0, v3, vcc
	v_lshl_add_u64 v[0:1], v[0:1], 0, v[8:9]
	v_add_co_u32_e32 v0, vcc, 0x1000, v0
	v_readlane_b32 s44, v234, 14
	s_nop 0
	v_addc_co_u32_e32 v1, vcc, 0, v1, vcc
	global_load_dwordx4 v[4:7], v[2:3], off offset:512
	s_nop 0
	global_load_dwordx4 v[0:3], v[0:1], off offset:512
